# speedup vs baseline: 1.0055x; 1.0033x over previous
.LBB0_1372:
	v_med3_i32 v118, v113, 0, v137
	v_lshlrev_b32_e32 v119, 2, v118
	global_load_dword v164, v119, s[54:55]
	s_add_i32 s40, s84, -2
	s_max_i32 s40, s40, 0
	s_lshl_b32 s12, s40, 13
	s_mov_b32 s13, 0
	s_lshl_b32 s24, s83, 13
	s_add_i32 m0, s74, s24
	v_lshl_add_u64 v[80:81], v[134:135], 0, s[12:13]
	global_load_lds_dwordx4 v[80:81], off
	s_lshl_b32 s12, s40, 14
	s_lshl_b32 s24, s83, 14
	s_add_i32 s24, s74, s24
	s_add_i32 m0, s24, 0x6000
	v_lshl_add_u64 v[80:81], v[132:133], 0, s[12:13]
	global_load_lds_dwordx4 v[80:81], off
	s_add_i32 m0, s24, 0x8000
	v_lshl_add_u64 v[80:81], v[80:81], 0, s[26:27]
	global_load_lds_dwordx4 v[80:81], off
	v_lshl_add_u32 v126, s81, 13, v153
	s_lshl_b32 s12, s81, 8
	v_add_u32_e32 v115, v126, v152
	v_add_u32_e32 v114, s12, v154
	v_add_u32_e32 v246, s12, v160
	ds_read_b32 v247, v246
	ds_read_b128 v[208:211], v115 offset:4096
	ds_read_b128 v[224:227], v115
	v_add_u32_e32 v116, v126, v155
	v_add_u32_e32 v117, v126, v156
	v_add_u32_e32 v118, v126, v157
	s_waitcnt lgkmcnt(1)
	v_mfma_f32_32x32x16_bf16 v[80:95], v[208:211], v[108:111], 0
	ds_read_b128 v[212:215], v116 offset:4096
	ds_read_b128 v[228:231], v116
	s_waitcnt lgkmcnt(2)
	v_mfma_f32_32x32x16_bf16 v[192:207], v[224:227], v[108:111], 0
	v_max_f32_dpp v248, v247, v247 quad_perm:[1,0,3,2] row_mask:0xf bank_mask:0xf
	ds_read_b128 v[216:219], v117 offset:4096
	ds_read_b128 v[232:235], v117
	s_waitcnt lgkmcnt(3)
	v_mfma_f32_32x32x16_bf16 v[80:95], v[212:215], v[104:107], v[80:95]
	s_nop 1
	v_max_f32_dpp v248, v248, v248 quad_perm:[2,3,0,1] row_mask:0xf bank_mask:0xf
	s_waitcnt lgkmcnt(2)
	v_mfma_f32_32x32x16_bf16 v[192:207], v[228:231], v[104:107], v[192:207]
	s_nop 1
	v_max_f32_dpp v248, v248, v248 row_half_mirror row_mask:0xf bank_mask:0xf
	ds_read_b128 v[220:223], v118 offset:4096
	ds_read_b128 v[236:239], v118
	s_waitcnt lgkmcnt(3)
	v_mfma_f32_32x32x16_bf16 v[80:95], v[216:219], v[100:103], v[80:95]
	s_nop 1
	v_max_f32_dpp v248, v248, v248 row_mirror row_mask:0xf bank_mask:0xf
	s_waitcnt lgkmcnt(2)
	v_mfma_f32_32x32x16_bf16 v[192:207], v[232:235], v[100:103], v[192:207]
	s_nop 1
	v_max_f32_dpp v248, v248, v248 row_bcast:15 row_mask:0xa bank_mask:0xf
	s_waitcnt lgkmcnt(1)
	v_mfma_f32_32x32x16_bf16 v[80:95], v[220:223], v[96:99], v[80:95]
	s_nop 1
	v_max_f32_dpp v248, v248, v248 row_bcast:31 row_mask:0xc bank_mask:0xf
	s_waitcnt lgkmcnt(0)
	v_mfma_f32_32x32x16_bf16 v[192:207], v[236:239], v[96:99], v[192:207]
	s_and_b64 vcc, exec, s[8:9]
	s_cbranch_vccnz .LBB0_1375
	v_sub_u32_e32 v242, v148, v131
	v_cvt_f32_i32_e32 v242, v242
	v_lshl_add_u32 v243, s80, 8, v160
	v_mul_f32_e32 v242, v139, v242
	ds_write_b32 v243, v242
.LBB0_1375:
	s_add_i32 s24, s84, -1
	s_mov_b32 s12, s80
	v_readlane_b32 s93, v248, 63
	s_nop 5
	v_max_f32_e32 v119, v81, v81
	v_max_f32_e32 v120, v80, v80
	v_max_f32_e32 v119, v120, v119
	v_max3_f32 v119, v119, v82, v83
	v_max_f32_e32 v240, v193, v193
	v_max_f32_e32 v241, v192, v192
	v_max3_f32 v119, v119, v84, v85
	v_max_f32_e32 v240, v241, v240
	v_max3_f32 v119, v119, v86, v87
	v_max3_f32 v240, v240, v194, v195
	v_max3_f32 v119, v119, v88, v89
	v_max3_f32 v240, v240, v196, v197
	v_max3_f32 v119, v119, v90, v91
	v_max3_f32 v240, v240, v198, v199
	v_max3_f32 v119, v119, v92, v93
	v_max3_f32 v240, v240, v200, v201
	v_max3_f32 v119, v119, v94, v95
	v_max3_f32 v240, v240, v202, v203
	v_max3_f32 v240, v240, v204, v205
	v_max3_f32 v240, v240, v206, v207
	v_add_f32_e32 v249, s93, v119
	v_cmp_lt_f32_e32 vcc, v249, v112
	s_cmp_eq_u64 vcc, exec
	s_cbranch_scc0 .LBB0_1377
	s_cmp_lt_i32 s84, 2
	s_waitcnt vmcnt(4) lgkmcnt(0)
	s_barrier
	v_subrev_u32_e32 v113, 64, v113
	s_mov_b64 s[42:43], 0
	s_mov_b64 s[40:41], s[10:11]
	s_waitcnt vmcnt(3)
	v_mov_b32_e32 v148, v164
	s_mov_b32 s80, s83
	s_mov_b32 s83, s81
	s_mov_b32 s84, 0
	s_cselect_b64 s[44:45], -1, 0
	s_mov_b32 s81, s12
	s_and_b64 vcc, exec, s[44:45]
	s_cbranch_vccz .LBB0_1378
	ds_read_b128 v[208:211], v114
	ds_read_b128 v[212:215], v114 offset:16
	ds_read_b128 v[216:219], v114 offset:64
	ds_read_b128 v[220:223], v114 offset:80
	s_waitcnt lgkmcnt(0)
	v_pk_add_f32 v[192:193], v[192:193], v[208:209]
	v_pk_add_f32 v[194:195], v[194:195], v[210:211]
	v_pk_add_f32 v[196:197], v[196:197], v[212:213]
	v_pk_add_f32 v[198:199], v[198:199], v[214:215]
	v_pk_add_f32 v[200:201], v[200:201], v[216:217]
	v_pk_add_f32 v[202:203], v[202:203], v[218:219]
	v_pk_add_f32 v[204:205], v[204:205], v[220:221]
	v_pk_add_f32 v[206:207], v[206:207], v[222:223]
	v_max_f32_e32 v240, v193, v193
	v_max_f32_e32 v241, v192, v192
	s_nop 0
	v_max_f32_e32 v240, v241, v240
	v_max3_f32 v240, v240, v194, v195
	v_max3_f32 v240, v240, v196, v197
	v_max3_f32 v240, v240, v198, v199
	v_max3_f32 v240, v240, v200, v201
	v_max3_f32 v240, v240, v202, v203
	v_max3_f32 v240, v240, v204, v205
	v_max3_f32 v240, v240, v206, v207
	v_mov_b32_e32 v241, v240
	s_nop 1
	v_permlane32_swap_b32_e32 v240, v241
	v_max_f32_e32 v241, v241, v241
	v_max_f32_e32 v240, v240, v240
	v_max_f32_e32 v166, v240, v241
	v_mov_b64_e32 v[64:65], v[192:193]
	v_mov_b64_e32 v[66:67], v[194:195]
	v_mov_b64_e32 v[68:69], v[196:197]
	v_mov_b64_e32 v[70:71], v[198:199]
	v_mov_b64_e32 v[72:73], v[200:201]
	v_mov_b64_e32 v[74:75], v[202:203]
	v_mov_b64_e32 v[76:77], v[204:205]
	v_mov_b64_e32 v[78:79], v[206:207]
	s_branch .LBB0_1330
